# scan nops removed + P2 MFMA-wave reorder + P1 silu tile balance (pn^2 rounds 2,3) + fox_jlo3 loads de-serialized
# speedup vs baseline: 1.0039x; 1.0002x over previous
.LBB0_141:
	s_ashr_i32 s4, s13, 3
	s_add_i32 s4, s22, s4
	s_ashr_i32 s5, s4, 31
	s_lshr_b32 s5, s5, 26
	s_add_i32 s5, s4, s5
	s_ashr_i32 s13, s5, 6
	s_lshl_b32 s13, s13, 2
	s_sub_i32 s15, 64, s13
	s_min_i32 s15, s15, 4
	s_abs_i32 s22, s15
	v_cvt_f32_u32_e32 v0, s22
	s_sub_i32 s24, 0, s22
	s_andn2_b32 s5, s5, 63
	s_sub_i32 s4, s4, s5
	v_rcp_iflag_f32_e32 v0, v0
	s_abs_i32 s5, s4
	s_xor_b32 s23, s4, s15
	s_ashr_i32 s23, s23, 31
	v_mul_f32_e32 v0, 0x4f7ffffe, v0
	v_cvt_u32_f32_e32 v0, v0
	s_nop 0
	v_readfirstlane_b32 s25, v0
	s_mul_i32 s24, s24, s25
	s_mul_hi_u32 s24, s25, s24
	s_add_i32 s25, s25, s24
	s_mul_hi_u32 s24, s5, s25
	s_mul_i32 s25, s24, s22
	s_sub_i32 s5, s5, s25
	s_add_i32 s26, s24, 1
	s_sub_i32 s25, s5, s22
	s_cmp_ge_u32 s5, s22
	s_cselect_b32 s24, s26, s24
	s_cselect_b32 s5, s25, s5
	s_add_i32 s25, s24, 1
	s_cmp_ge_u32 s5, s22
	s_cselect_b32 s5, s25, s24
	s_xor_b32 s5, s5, s23
	s_sub_i32 s68, s5, s23
	s_mul_i32 s5, s68, s15
	s_sub_i32 s4, s4, s5
	s_add_i32 s86, s13, s4
	s_lshr_b32 s4, s88, 1
	s_and_b32 s4, s4, 1
	s_lshl_b32 s4, s4, 1
	s_xor_b32 s68, s68, s4

.LBB0_325:
	v_lshl_add_u64 v[98:99], v[94:95], 0, s[4:5]
	v_add_co_u32_e32 v0, vcc, 0x9d30000, v98
	s_waitcnt lgkmcnt(0)
	s_barrier
	v_lshl_add_u64 v[106:107], v[96:97], 0, s[4:5]
	s_nop 0
	v_addc_co_u32_e32 v1, vcc, 0, v99, vcc
	s_mul_i32 s98, s13, 0x2800
	v_add_u32_e32 v192, s98, v108
	ds_read_b128 v[120:123], v192 offset:18432
	ds_read_b128 v[124:127], v192 offset:23552
	ds_read_b128 v[128:131], v192 offset:18496
	ds_read_b128 v[132:135], v192 offset:23616
	s_waitcnt lgkmcnt(3)
	v_mfma_f32_16x16x32_bf16 v[120:123], v[16:19], v[120:123], 0
	s_waitcnt lgkmcnt(2)
	v_mfma_f32_16x16x32_bf16 v[124:127], v[16:19], v[124:127], 0
	s_waitcnt lgkmcnt(1)
	v_mfma_f32_16x16x32_bf16 v[120:123], v[20:23], v[128:131], v[120:123]
	s_waitcnt lgkmcnt(0)
	v_mfma_f32_16x16x32_bf16 v[124:127], v[20:23], v[132:135], v[124:127]
	ds_read_b128 v[128:131], v192 offset:18560
	ds_read_b128 v[132:135], v192 offset:23680
	s_waitcnt lgkmcnt(1)
	v_mfma_f32_16x16x32_bf16 v[120:123], v[24:27], v[128:131], v[120:123]
	s_waitcnt lgkmcnt(0)
	v_mfma_f32_16x16x32_bf16 v[124:127], v[24:27], v[132:135], v[124:127]
	ds_read_b128 v[128:131], v192 offset:18624
	ds_read_b128 v[132:135], v192 offset:23744
	s_waitcnt lgkmcnt(1)
	v_mfma_f32_16x16x32_bf16 v[120:123], v[32:35], v[128:131], v[120:123]
	s_waitcnt lgkmcnt(0)
	v_mfma_f32_16x16x32_bf16 v[124:127], v[32:35], v[132:135], v[124:127]
	s_waitcnt lgkmcnt(0)
	s_barrier
	v_add_co_u32_e32 v2, vcc, 0x9d3c000, v98
	global_load_dwordx4 v[60:63], v[106:107], off
	s_nop 0
	v_addc_co_u32_e32 v3, vcc, 0, v99, vcc
	global_load_dwordx2 v[104:105], v[0:1], off
	global_load_dwordx2 v[102:103], v[2:3], off
	s_waitcnt vmcnt(8)
	v_mfma_f32_32x32x16_bf16 v[128:143], v[56:59], v[28:31], 0
	v_mfma_f32_32x32x16_bf16 v[144:159], v[56:59], v[40:43], 0
	v_mfma_f32_32x32x16_bf16 v[160:175], v[56:59], v[44:47], 0
	v_mfma_f32_32x32x16_bf16 v[176:191], v[56:59], v[48:51], 0
	s_mul_i32 s24, s13, 0x2800
	v_add_u32_e32 v85, s24, v108
	s_xor_b32 s13, s13, 1
	s_nop 8
	ds_write_b128 v71, v[128:131]
	ds_write_b128 v71, v[132:135] offset:32
	ds_write_b128 v71, v[136:139] offset:64
	ds_write_b128 v71, v[140:143] offset:96
	ds_write_b128 v71, v[144:147] offset:4608
	ds_write_b128 v71, v[148:151] offset:4640
	ds_write_b128 v71, v[152:155] offset:4672
	ds_write_b128 v71, v[156:159] offset:4704
	ds_write_b128 v71, v[160:163] offset:9216
	ds_write_b128 v71, v[164:167] offset:9248
	ds_write_b128 v71, v[168:171] offset:9280
	ds_write_b128 v71, v[172:175] offset:9312
	ds_write_b128 v71, v[176:179] offset:13824
	ds_write_b128 v71, v[180:183] offset:13856
	ds_write_b128 v71, v[184:187] offset:13888
	ds_write_b128 v71, v[188:191] offset:13920
	v_mov_b32_e32 v0, v120
	v_mov_b32_e32 v1, v121
	v_mov_b32_e32 v2, v122
	v_mov_b32_e32 v3, v123
	v_mov_b32_e32 v4, v124
	v_mov_b32_e32 v5, v125
	v_mov_b32_e32 v6, v126
	v_mov_b32_e32 v7, v127
	s_waitcnt vmcnt(7)
	v_lshlrev_b32_e32 v8, 16, v92
	s_nop 3
	v_fma_f32 v0, v36, v8, v0
	v_and_b32_e32 v8, 0xffff0000, v92
	v_fma_f32 v1, v37, v8, v1
	v_lshlrev_b32_e32 v8, 16, v93
	v_fma_f32 v8, v38, v8, v2
	v_and_b32_e32 v2, 0xffff0000, v93
	v_fmac_f32_e32 v3, v39, v2
	s_waitcnt vmcnt(6)
	v_lshlrev_b32_e32 v2, 16, v100
	v_fma_f32 v4, v36, v2, v4
	v_and_b32_e32 v2, 0xffff0000, v100
	v_fma_f32 v5, v37, v2, v5
	v_lshlrev_b32_e32 v2, 16, v101
	v_fma_f32 v6, v38, v2, v6
	v_and_b32_e32 v2, 0xffff0000, v101
	v_fmac_f32_e32 v7, v39, v2
	v_mul_f32_e32 v2, v0, v0
	v_fmamk_f32 v2, v2, 0xbdd2d3e8, v111
	v_mul_f32_e32 v2, v0, v2
	v_exp_f32_e32 v2, v2
	s_nop 0
	v_add_f32_e32 v2, 1.0, v2
	v_rcp_f32_e32 v2, v2
	s_nop 0
	v_mul_f32_e32 v0, v0, v2
	v_mul_f32_e32 v2, v1, v1
	v_fmamk_f32 v2, v2, 0xbdd2d3e8, v111
	v_mul_f32_e32 v2, v1, v2
	v_exp_f32_e32 v2, v2
	s_nop 0
	v_add_f32_e32 v2, 1.0, v2
	v_rcp_f32_e32 v2, v2
	s_nop 0
	v_mul_f32_e32 v1, v1, v2
	v_cvt_pk_bf16_f32 v2, v0, v1
	v_mul_f32_e32 v0, v8, v8
	v_mul_f32_e32 v1, v3, v3
	v_fmamk_f32 v0, v0, 0xbdd2d3e8, v111
	v_fmamk_f32 v1, v1, 0xbdd2d3e8, v111
	v_mul_f32_e32 v0, v8, v0
	v_mul_f32_e32 v1, v3, v1
	v_exp_f32_e32 v0, v0
	v_exp_f32_e32 v1, v1
	v_add_f32_e32 v0, 1.0, v0
	v_add_f32_e32 v1, 1.0, v1
	v_rcp_f32_e32 v0, v0
	v_rcp_f32_e32 v1, v1
	v_mul_f32_e32 v0, v8, v0
	v_mul_f32_e32 v1, v3, v1
	v_cvt_pk_bf16_f32 v3, v0, v1
	v_mul_f32_e32 v0, v4, v4
	v_mul_f32_e32 v1, v5, v5
	v_fmamk_f32 v0, v0, 0xbdd2d3e8, v111
	v_fmamk_f32 v1, v1, 0xbdd2d3e8, v111
	v_mul_f32_e32 v0, v4, v0
	v_mul_f32_e32 v1, v5, v1
	v_exp_f32_e32 v0, v0
	v_exp_f32_e32 v1, v1
	v_add_f32_e32 v0, 1.0, v0
	v_add_f32_e32 v1, 1.0, v1
	v_rcp_f32_e32 v0, v0
	v_rcp_f32_e32 v1, v1
	v_mul_f32_e32 v0, v4, v0
	v_mul_f32_e32 v1, v5, v1
	v_cvt_pk_bf16_f32 v0, v0, v1
	v_mul_f32_e32 v1, v6, v6
	v_mul_f32_e32 v4, v7, v7
	v_fmamk_f32 v1, v1, 0xbdd2d3e8, v111
	v_fmamk_f32 v4, v4, 0xbdd2d3e8, v111
	v_mul_f32_e32 v1, v6, v1
	v_mul_f32_e32 v4, v7, v4
	v_exp_f32_e32 v1, v1
	v_exp_f32_e32 v4, v4
	v_add_f32_e32 v1, 1.0, v1
	v_add_f32_e32 v4, 1.0, v4
	v_rcp_f32_e32 v1, v1
	v_rcp_f32_e32 v4, v4
	v_mul_f32_e32 v1, v6, v1
	v_mul_f32_e32 v4, v7, v4
	v_cvt_pk_bf16_f32 v1, v1, v4
	v_add_co_u32_e32 v4, vcc, s22, v98
	s_nop 1
	v_addc_co_u32_e32 v5, vcc, 0, v99, vcc
	global_store_dwordx2 v[4:5], v[2:3], off
	v_add_co_u32_e32 v2, vcc, s23, v98
	s_nop 1
	v_addc_co_u32_e32 v3, vcc, 0, v99, vcc
	global_store_dwordx2 v[2:3], v[0:1], off
	s_waitcnt lgkmcnt(0)
	s_barrier
	v_add_co_u32_e32 v0, vcc, s20, v106
	s_mul_i32 s98, s13, 0x2800
	v_add_u32_e32 v193, s98, v108
	ds_read_b128 v[120:123], v193 offset:18432
	ds_read_b128 v[124:127], v193 offset:23552
	ds_read_b128 v[128:131], v193 offset:18496
	ds_read_b128 v[132:135], v193 offset:23616
	s_waitcnt lgkmcnt(3)
	v_mfma_f32_16x16x32_bf16 v[120:123], v[16:19], v[120:123], 0
	s_waitcnt lgkmcnt(2)
	v_mfma_f32_16x16x32_bf16 v[124:127], v[16:19], v[124:127], 0
	s_waitcnt lgkmcnt(1)
	v_mfma_f32_16x16x32_bf16 v[120:123], v[20:23], v[128:131], v[120:123]
	s_waitcnt lgkmcnt(0)
	v_mfma_f32_16x16x32_bf16 v[124:127], v[20:23], v[132:135], v[124:127]
	ds_read_b128 v[128:131], v193 offset:18560
	ds_read_b128 v[132:135], v193 offset:23680
	s_waitcnt lgkmcnt(1)
	v_mfma_f32_16x16x32_bf16 v[120:123], v[24:27], v[128:131], v[120:123]
	s_waitcnt lgkmcnt(0)
	v_mfma_f32_16x16x32_bf16 v[124:127], v[24:27], v[132:135], v[124:127]
	ds_read_b128 v[128:131], v193 offset:18624
	ds_read_b128 v[132:135], v193 offset:23744
	s_waitcnt lgkmcnt(1)
	v_mfma_f32_16x16x32_bf16 v[120:123], v[32:35], v[128:131], v[120:123]
	s_waitcnt lgkmcnt(0)
	v_mfma_f32_16x16x32_bf16 v[124:127], v[32:35], v[132:135], v[124:127]
	s_waitcnt lgkmcnt(0)
	s_barrier
	s_nop 1
	v_addc_co_u32_e32 v1, vcc, 0, v107, vcc
	global_load_dwordx4 v[56:59], v[0:1], off
	v_add_co_u32_e32 v0, vcc, s33, v98
	s_nop 1
	v_addc_co_u32_e32 v1, vcc, 0, v99, vcc
	v_add_co_u32_e32 v2, vcc, s44, v98
	s_nop 1
	v_addc_co_u32_e32 v3, vcc, 0, v99, vcc
	global_load_dwordx2 v[92:93], v[0:1], off
	global_load_dwordx2 v[100:101], v[2:3], off
	s_waitcnt vmcnt(10)
	v_mfma_f32_32x32x16_bf16 v[128:143], v[52:55], v[28:31], 0
	v_mfma_f32_32x32x16_bf16 v[144:159], v[52:55], v[40:43], 0
	v_mfma_f32_32x32x16_bf16 v[160:175], v[52:55], v[44:47], 0
	v_mfma_f32_32x32x16_bf16 v[176:191], v[52:55], v[48:51], 0
	s_mul_i32 s24, s13, 0x2800
	v_add_u32_e32 v52, s24, v108
	s_nop 8
	ds_write_b128 v71, v[128:131]
	ds_write_b128 v71, v[132:135] offset:32
	ds_write_b128 v71, v[136:139] offset:64
	ds_write_b128 v71, v[140:143] offset:96
	ds_write_b128 v71, v[144:147] offset:4608
	ds_write_b128 v71, v[148:151] offset:4640
	ds_write_b128 v71, v[152:155] offset:4672
	ds_write_b128 v71, v[156:159] offset:4704
	ds_write_b128 v71, v[160:163] offset:9216
	ds_write_b128 v71, v[164:167] offset:9248
	ds_write_b128 v71, v[168:171] offset:9280
	ds_write_b128 v71, v[172:175] offset:9312
	ds_write_b128 v71, v[176:179] offset:13824
	ds_write_b128 v71, v[180:183] offset:13856
	ds_write_b128 v71, v[184:187] offset:13888
	ds_write_b128 v71, v[188:191] offset:13920
	v_mov_b32_e32 v0, v120
	v_mov_b32_e32 v1, v121
	v_mov_b32_e32 v2, v122
	v_mov_b32_e32 v3, v123
	v_mov_b32_e32 v4, v124
	v_mov_b32_e32 v5, v125
	v_mov_b32_e32 v6, v126
	v_mov_b32_e32 v7, v127
	s_waitcnt vmcnt(9)
	v_lshlrev_b32_e32 v8, 16, v88
	s_nop 3
	v_fma_f32 v0, v36, v8, v0
	v_and_b32_e32 v8, 0xffff0000, v88
	v_fma_f32 v1, v37, v8, v1
	v_lshlrev_b32_e32 v8, 16, v89
	v_fma_f32 v2, v38, v8, v2
	v_and_b32_e32 v8, 0xffff0000, v89
	v_fmac_f32_e32 v3, v39, v8
	s_waitcnt vmcnt(8)
	v_lshlrev_b32_e32 v8, 16, v90
	v_fma_f32 v4, v36, v8, v4
	v_and_b32_e32 v8, 0xffff0000, v90
	v_fma_f32 v5, v37, v8, v5
	v_lshlrev_b32_e32 v8, 16, v91
	v_fma_f32 v6, v38, v8, v6
	v_and_b32_e32 v8, 0xffff0000, v91
	v_fmac_f32_e32 v7, v39, v8
	v_mul_f32_e32 v8, v0, v0
	v_fmamk_f32 v8, v8, 0xbdd2d3e8, v111
	v_mul_f32_e32 v8, v0, v8
	v_exp_f32_e32 v8, v8
	s_nop 0
	v_add_f32_e32 v8, 1.0, v8
	v_rcp_f32_e32 v8, v8
	s_nop 0
	v_mul_f32_e32 v0, v0, v8
	v_mul_f32_e32 v8, v1, v1
	v_fmamk_f32 v8, v8, 0xbdd2d3e8, v111
	v_mul_f32_e32 v8, v1, v8
	v_exp_f32_e32 v8, v8
	s_nop 0
	v_add_f32_e32 v8, 1.0, v8
	v_rcp_f32_e32 v8, v8
	s_nop 0
	v_mul_f32_e32 v1, v1, v8
	v_cvt_pk_bf16_f32 v0, v0, v1
	v_mul_f32_e32 v1, v2, v2
	v_fmamk_f32 v1, v1, 0xbdd2d3e8, v111
	v_mul_f32_e32 v1, v2, v1
	v_exp_f32_e32 v1, v1
	s_nop 0
	v_add_f32_e32 v1, 1.0, v1
	v_rcp_f32_e32 v1, v1
	s_nop 0
	v_mul_f32_e32 v1, v2, v1
	v_mul_f32_e32 v2, v3, v3
	v_fmamk_f32 v2, v2, 0xbdd2d3e8, v111
	v_mul_f32_e32 v2, v3, v2
	v_exp_f32_e32 v2, v2
	s_nop 0
	v_add_f32_e32 v2, 1.0, v2
	v_rcp_f32_e32 v2, v2
	s_nop 0
	v_mul_f32_e32 v2, v3, v2
	v_cvt_pk_bf16_f32 v1, v1, v2
	v_mul_f32_e32 v2, v4, v4
	v_mul_f32_e32 v3, v5, v5
	v_fmamk_f32 v2, v2, 0xbdd2d3e8, v111
	v_fmamk_f32 v3, v3, 0xbdd2d3e8, v111
	v_mul_f32_e32 v2, v4, v2
	v_mul_f32_e32 v3, v5, v3
	v_exp_f32_e32 v2, v2
	v_exp_f32_e32 v3, v3
	v_add_f32_e32 v2, 1.0, v2
	v_add_f32_e32 v3, 1.0, v3
	v_rcp_f32_e32 v2, v2
	v_rcp_f32_e32 v3, v3
	v_mul_f32_e32 v2, v4, v2
	v_mul_f32_e32 v3, v5, v3
	v_cvt_pk_bf16_f32 v2, v2, v3
	v_mul_f32_e32 v3, v6, v6
	v_mul_f32_e32 v4, v7, v7
	v_fmamk_f32 v3, v3, 0xbdd2d3e8, v111
	v_fmamk_f32 v4, v4, 0xbdd2d3e8, v111
	v_mul_f32_e32 v3, v6, v3
	v_mul_f32_e32 v4, v7, v4
	v_exp_f32_e32 v3, v3
	v_exp_f32_e32 v4, v4
	v_add_f32_e32 v3, 1.0, v3
	v_add_f32_e32 v4, 1.0, v4
	v_rcp_f32_e32 v3, v3
	v_rcp_f32_e32 v4, v4
	v_mul_f32_e32 v3, v6, v3
	v_mul_f32_e32 v4, v7, v4
	v_cvt_pk_bf16_f32 v3, v3, v4
	v_add_co_u32_e32 v4, vcc, s45, v98
	s_nop 1
	v_addc_co_u32_e32 v5, vcc, 0, v99, vcc
	global_store_dwordx2 v[4:5], v[0:1], off
	v_add_co_u32_e32 v0, vcc, s46, v98
	s_nop 1
	v_addc_co_u32_e32 v1, vcc, 0, v99, vcc
	global_store_dwordx2 v[0:1], v[2:3], off
	s_waitcnt lgkmcnt(0)
	s_barrier
	v_add_co_u32_e32 v0, vcc, s21, v106
	ds_read_b128 v[120:123], v192 offset:18432
	ds_read_b128 v[124:127], v192 offset:23552
	ds_read_b128 v[128:131], v192 offset:18496
	ds_read_b128 v[132:135], v192 offset:23616
	s_waitcnt lgkmcnt(3)
	v_mfma_f32_16x16x32_bf16 v[120:123], v[16:19], v[120:123], 0
	s_waitcnt lgkmcnt(2)
	v_mfma_f32_16x16x32_bf16 v[124:127], v[16:19], v[124:127], 0
	s_waitcnt lgkmcnt(1)
	v_mfma_f32_16x16x32_bf16 v[120:123], v[20:23], v[128:131], v[120:123]
	s_waitcnt lgkmcnt(0)
	v_mfma_f32_16x16x32_bf16 v[124:127], v[20:23], v[132:135], v[124:127]
	ds_read_b128 v[128:131], v192 offset:18560
	ds_read_b128 v[132:135], v192 offset:23680
	s_waitcnt lgkmcnt(1)
	v_mfma_f32_16x16x32_bf16 v[120:123], v[24:27], v[128:131], v[120:123]
	s_waitcnt lgkmcnt(0)
	v_mfma_f32_16x16x32_bf16 v[124:127], v[24:27], v[132:135], v[124:127]
	ds_read_b128 v[128:131], v192 offset:18624
	ds_read_b128 v[132:135], v192 offset:23744
	s_waitcnt lgkmcnt(1)
	v_mfma_f32_16x16x32_bf16 v[120:123], v[32:35], v[128:131], v[120:123]
	s_waitcnt lgkmcnt(0)
	v_mfma_f32_16x16x32_bf16 v[124:127], v[32:35], v[132:135], v[124:127]
	s_waitcnt lgkmcnt(0)
	s_barrier
	s_mov_b32 s24, 0x9d60000
	s_nop 0
	v_addc_co_u32_e32 v1, vcc, 0, v107, vcc
	global_load_dwordx4 v[52:55], v[0:1], off
	v_add_co_u32_e32 v0, vcc, s24, v98
	s_mov_b32 s24, 0x9d6c000
	s_nop 0
	v_addc_co_u32_e32 v1, vcc, 0, v99, vcc
	v_add_co_u32_e32 v2, vcc, s24, v98
	s_nop 1
	v_addc_co_u32_e32 v3, vcc, 0, v99, vcc
	global_load_dwordx2 v[88:89], v[0:1], off
	global_load_dwordx2 v[90:91], v[2:3], off
	s_waitcnt vmcnt(12)
	v_mfma_f32_32x32x16_bf16 v[128:143], v[60:63], v[28:31], 0
	v_mfma_f32_32x32x16_bf16 v[144:159], v[60:63], v[40:43], 0
	v_mfma_f32_32x32x16_bf16 v[160:175], v[60:63], v[44:47], 0
	v_mfma_f32_32x32x16_bf16 v[176:191], v[60:63], v[48:51], 0
	s_nop 8
	ds_write_b128 v71, v[128:131]
	ds_write_b128 v71, v[132:135] offset:32
	ds_write_b128 v71, v[136:139] offset:64
	ds_write_b128 v71, v[140:143] offset:96
	ds_write_b128 v71, v[144:147] offset:4608
	ds_write_b128 v71, v[148:151] offset:4640
	ds_write_b128 v71, v[152:155] offset:4672
	ds_write_b128 v71, v[156:159] offset:4704
	ds_write_b128 v71, v[160:163] offset:9216
	ds_write_b128 v71, v[164:167] offset:9248
	ds_write_b128 v71, v[168:171] offset:9280
	ds_write_b128 v71, v[172:175] offset:9312
	ds_write_b128 v71, v[176:179] offset:13824
	ds_write_b128 v71, v[180:183] offset:13856
	ds_write_b128 v71, v[184:187] offset:13888
	ds_write_b128 v71, v[188:191] offset:13920
	v_mov_b32_e32 v0, v120
	v_mov_b32_e32 v1, v121
	v_mov_b32_e32 v2, v122
	v_mov_b32_e32 v3, v123
	v_mov_b32_e32 v4, v124
	v_mov_b32_e32 v5, v125
	v_mov_b32_e32 v6, v126
	v_mov_b32_e32 v7, v127
	s_waitcnt vmcnt(11)
	v_lshlrev_b32_e32 v8, 16, v104
	s_nop 3
	v_fma_f32 v0, v36, v8, v0
	v_and_b32_e32 v8, 0xffff0000, v104
	v_fma_f32 v1, v37, v8, v1
	v_lshlrev_b32_e32 v8, 16, v105
	v_fma_f32 v2, v38, v8, v2
	v_and_b32_e32 v8, 0xffff0000, v105
	v_fmac_f32_e32 v3, v39, v8
	s_waitcnt vmcnt(10)
	v_lshlrev_b32_e32 v8, 16, v102
	v_fma_f32 v4, v36, v8, v4
	v_and_b32_e32 v8, 0xffff0000, v102
	v_fma_f32 v5, v37, v8, v5
	v_lshlrev_b32_e32 v8, 16, v103
	v_fma_f32 v6, v38, v8, v6
	v_and_b32_e32 v8, 0xffff0000, v103
	v_fmac_f32_e32 v7, v39, v8
	v_mul_f32_e32 v8, v0, v0
	v_fmamk_f32 v8, v8, 0xbdd2d3e8, v111
	v_mul_f32_e32 v8, v0, v8
	v_exp_f32_e32 v8, v8
	s_nop 0
	v_add_f32_e32 v8, 1.0, v8
	v_rcp_f32_e32 v8, v8
	s_nop 0
	v_mul_f32_e32 v0, v0, v8
	v_mul_f32_e32 v8, v1, v1
	v_fmamk_f32 v8, v8, 0xbdd2d3e8, v111
	v_mul_f32_e32 v8, v1, v8
	v_exp_f32_e32 v8, v8
	s_nop 0
	v_add_f32_e32 v8, 1.0, v8
	v_rcp_f32_e32 v8, v8
	s_nop 0
	v_mul_f32_e32 v1, v1, v8
	v_cvt_pk_bf16_f32 v0, v0, v1
	v_mul_f32_e32 v1, v2, v2
	v_fmamk_f32 v1, v1, 0xbdd2d3e8, v111
	v_mul_f32_e32 v1, v2, v1
	v_exp_f32_e32 v1, v1
	s_nop 0
	v_add_f32_e32 v1, 1.0, v1
	v_rcp_f32_e32 v1, v1
	s_nop 0
	v_mul_f32_e32 v1, v2, v1
	v_mul_f32_e32 v2, v3, v3
	v_fmamk_f32 v2, v2, 0xbdd2d3e8, v111
	v_mul_f32_e32 v2, v3, v2
	v_exp_f32_e32 v2, v2
	s_nop 0
	v_add_f32_e32 v2, 1.0, v2
	v_rcp_f32_e32 v2, v2
	s_nop 0
	v_mul_f32_e32 v2, v3, v2
	v_cvt_pk_bf16_f32 v1, v1, v2
	v_mul_f32_e32 v2, v4, v4
	v_mul_f32_e32 v3, v5, v5
	v_fmamk_f32 v2, v2, 0xbdd2d3e8, v111
	v_fmamk_f32 v3, v3, 0xbdd2d3e8, v111
	v_mul_f32_e32 v2, v4, v2
	v_mul_f32_e32 v3, v5, v3
	v_exp_f32_e32 v2, v2
	v_exp_f32_e32 v3, v3
	v_add_f32_e32 v2, 1.0, v2
	v_add_f32_e32 v3, 1.0, v3
	v_rcp_f32_e32 v2, v2
	v_rcp_f32_e32 v3, v3
	v_mul_f32_e32 v2, v4, v2
	v_mul_f32_e32 v3, v5, v3
	v_cvt_pk_bf16_f32 v2, v2, v3
	v_mul_f32_e32 v3, v6, v6
	v_mul_f32_e32 v4, v7, v7
	v_fmamk_f32 v3, v3, 0xbdd2d3e8, v111
	v_fmamk_f32 v4, v4, 0xbdd2d3e8, v111
	v_mul_f32_e32 v3, v6, v3
	v_mul_f32_e32 v4, v7, v4
	v_exp_f32_e32 v3, v3
	v_exp_f32_e32 v4, v4
	v_add_f32_e32 v3, 1.0, v3
	v_add_f32_e32 v4, 1.0, v4
	v_rcp_f32_e32 v3, v3
	v_rcp_f32_e32 v4, v4
	v_mul_f32_e32 v3, v6, v3
	v_mul_f32_e32 v4, v7, v4
	v_cvt_pk_bf16_f32 v3, v3, v4
	v_add_co_u32_e32 v4, vcc, s47, v98
	s_nop 1
	v_addc_co_u32_e32 v5, vcc, 0, v99, vcc
	global_store_dwordx2 v[4:5], v[0:1], off
	v_add_co_u32_e32 v0, vcc, 0x11d3c000, v98
	s_nop 1
	v_addc_co_u32_e32 v1, vcc, 0, v99, vcc
	global_store_dwordx2 v[0:1], v[2:3], off
	s_add_i32 s12, s12, 3
	v_lshl_add_u64 v[94:95], v[94:95], 0, s[40:41]
	s_cmp_gt_u32 s12, 57
	v_lshl_add_u64 v[96:97], v[96:97], 0, s[40:41]
	s_cbranch_scc0 .LBB0_325
	v_lshl_add_u64 v[60:61], v[94:95], 0, s[4:5]
	v_add_co_u32_e32 v0, vcc, 0x9d30000, v60
	s_waitcnt lgkmcnt(0)
	s_barrier
	ds_read_b128 v[120:123], v108 offset:18432
	ds_read_b128 v[124:127], v108 offset:23552
	ds_read_b128 v[128:131], v108 offset:18496
	ds_read_b128 v[132:135], v108 offset:23616
	s_waitcnt lgkmcnt(3)
	v_mfma_f32_16x16x32_bf16 v[120:123], v[16:19], v[120:123], 0
	s_waitcnt lgkmcnt(2)
	v_mfma_f32_16x16x32_bf16 v[124:127], v[16:19], v[124:127], 0
	s_waitcnt lgkmcnt(1)
	v_mfma_f32_16x16x32_bf16 v[120:123], v[20:23], v[128:131], v[120:123]
	s_waitcnt lgkmcnt(0)
	v_mfma_f32_16x16x32_bf16 v[124:127], v[20:23], v[132:135], v[124:127]
	ds_read_b128 v[128:131], v108 offset:18560
	ds_read_b128 v[132:135], v108 offset:23680
	s_waitcnt lgkmcnt(1)
	v_mfma_f32_16x16x32_bf16 v[120:123], v[24:27], v[128:131], v[120:123]
	s_waitcnt lgkmcnt(0)
	v_mfma_f32_16x16x32_bf16 v[124:127], v[24:27], v[132:135], v[124:127]
	ds_read_b128 v[128:131], v108 offset:18624
	ds_read_b128 v[132:135], v108 offset:23744
	s_waitcnt lgkmcnt(1)
	v_mfma_f32_16x16x32_bf16 v[120:123], v[32:35], v[128:131], v[120:123]
	s_waitcnt lgkmcnt(0)
	v_mfma_f32_16x16x32_bf16 v[124:127], v[32:35], v[132:135], v[124:127]
	s_waitcnt lgkmcnt(0)
	s_barrier
	s_nop 1
	v_addc_co_u32_e32 v1, vcc, 0, v61, vcc
	v_add_co_u32_e32 v2, vcc, 0x9d3c000, v60
	s_nop 1
	v_addc_co_u32_e32 v3, vcc, 0, v61, vcc
	global_load_dwordx2 v[94:95], v[0:1], off
	global_load_dwordx2 v[62:63], v[2:3], off
	s_waitcnt vmcnt(11)
	v_mfma_f32_32x32x16_bf16 v[128:143], v[56:59], v[28:31], 0
	v_mfma_f32_32x32x16_bf16 v[144:159], v[56:59], v[40:43], 0
	v_mfma_f32_32x32x16_bf16 v[160:175], v[56:59], v[44:47], 0
	v_mfma_f32_32x32x16_bf16 v[176:191], v[56:59], v[48:51], 0
	s_nop 8
	ds_write_b128 v71, v[128:131]
	ds_write_b128 v71, v[132:135] offset:32
	ds_write_b128 v71, v[136:139] offset:64
	ds_write_b128 v71, v[140:143] offset:96
	ds_write_b128 v71, v[144:147] offset:4608
	ds_write_b128 v71, v[148:151] offset:4640
	ds_write_b128 v71, v[152:155] offset:4672
	ds_write_b128 v71, v[156:159] offset:4704
	ds_write_b128 v71, v[160:163] offset:9216
	ds_write_b128 v71, v[164:167] offset:9248
	ds_write_b128 v71, v[168:171] offset:9280
	ds_write_b128 v71, v[172:175] offset:9312
	ds_write_b128 v71, v[176:179] offset:13824
	ds_write_b128 v71, v[180:183] offset:13856
	ds_write_b128 v71, v[184:187] offset:13888
	ds_write_b128 v71, v[188:191] offset:13920
	v_mov_b32_e32 v0, v120
	v_mov_b32_e32 v1, v121
	v_mov_b32_e32 v2, v122
	v_mov_b32_e32 v3, v123
	v_mov_b32_e32 v4, v124
	v_mov_b32_e32 v5, v125
	v_mov_b32_e32 v6, v126
	v_mov_b32_e32 v7, v127
	s_waitcnt vmcnt(10)
	v_lshlrev_b32_e32 v8, 16, v92
	s_nop 3
	v_fma_f32 v0, v36, v8, v0
	v_and_b32_e32 v8, 0xffff0000, v92
	v_fma_f32 v1, v37, v8, v1
	v_lshlrev_b32_e32 v8, 16, v93
	v_fma_f32 v2, v38, v8, v2
	v_and_b32_e32 v8, 0xffff0000, v93
	v_fmac_f32_e32 v3, v39, v8
	s_waitcnt vmcnt(9)
	v_lshlrev_b32_e32 v8, 16, v100
	v_fma_f32 v4, v36, v8, v4
	v_and_b32_e32 v8, 0xffff0000, v100
	v_fma_f32 v5, v37, v8, v5
	v_lshlrev_b32_e32 v8, 16, v101
	v_fma_f32 v6, v38, v8, v6
	v_and_b32_e32 v8, 0xffff0000, v101
	v_fmac_f32_e32 v7, v39, v8
	v_mul_f32_e32 v8, v0, v0
	v_fmamk_f32 v8, v8, 0xbdd2d3e8, v111
	v_mul_f32_e32 v8, v0, v8
	v_exp_f32_e32 v8, v8
	s_nop 0
	v_add_f32_e32 v8, 1.0, v8
	v_rcp_f32_e32 v8, v8
	s_nop 0
	v_mul_f32_e32 v0, v0, v8
	v_mul_f32_e32 v8, v1, v1
	v_fmamk_f32 v8, v8, 0xbdd2d3e8, v111
	v_mul_f32_e32 v8, v1, v8
	v_exp_f32_e32 v8, v8
	s_nop 0
	v_add_f32_e32 v8, 1.0, v8
	v_rcp_f32_e32 v8, v8
	s_nop 0
	v_mul_f32_e32 v1, v1, v8
	v_cvt_pk_bf16_f32 v0, v0, v1
	v_mul_f32_e32 v1, v2, v2
	v_fmamk_f32 v1, v1, 0xbdd2d3e8, v111
	v_mul_f32_e32 v1, v2, v1
	v_exp_f32_e32 v1, v1
	s_nop 0
	v_add_f32_e32 v1, 1.0, v1
	v_rcp_f32_e32 v1, v1
	s_nop 0
	v_mul_f32_e32 v1, v2, v1
	v_mul_f32_e32 v2, v3, v3
	v_fmamk_f32 v2, v2, 0xbdd2d3e8, v111
	v_mul_f32_e32 v2, v3, v2
	v_exp_f32_e32 v2, v2
	s_nop 0
	v_add_f32_e32 v2, 1.0, v2
	v_rcp_f32_e32 v2, v2
	s_nop 0
	v_mul_f32_e32 v2, v3, v2
	v_cvt_pk_bf16_f32 v1, v1, v2
	v_mul_f32_e32 v2, v4, v4
	v_mul_f32_e32 v3, v5, v5
	v_fmamk_f32 v2, v2, 0xbdd2d3e8, v111
	v_fmamk_f32 v3, v3, 0xbdd2d3e8, v111
	v_mul_f32_e32 v2, v4, v2
	v_mul_f32_e32 v3, v5, v3
	v_exp_f32_e32 v2, v2
	v_exp_f32_e32 v3, v3
	v_add_f32_e32 v2, 1.0, v2
	v_add_f32_e32 v3, 1.0, v3
	v_rcp_f32_e32 v2, v2
	v_rcp_f32_e32 v3, v3
	v_mul_f32_e32 v2, v4, v2
	v_mul_f32_e32 v3, v5, v3
	v_cvt_pk_bf16_f32 v2, v2, v3
	v_mul_f32_e32 v3, v6, v6
	v_mul_f32_e32 v4, v7, v7
	v_fmamk_f32 v3, v3, 0xbdd2d3e8, v111
	v_fmamk_f32 v4, v4, 0xbdd2d3e8, v111
	v_mul_f32_e32 v3, v6, v3
	v_mul_f32_e32 v4, v7, v4
	v_exp_f32_e32 v3, v3
	v_exp_f32_e32 v4, v4
	v_add_f32_e32 v3, 1.0, v3
	v_add_f32_e32 v4, 1.0, v4
	v_rcp_f32_e32 v3, v3
	v_rcp_f32_e32 v4, v4
	v_mul_f32_e32 v3, v6, v3
	v_mul_f32_e32 v4, v7, v4
	v_cvt_pk_bf16_f32 v3, v3, v4
	v_add_co_u32_e32 v4, vcc, s22, v60
	s_nop 1
	v_addc_co_u32_e32 v5, vcc, 0, v61, vcc
	global_store_dwordx2 v[4:5], v[0:1], off
	v_add_co_u32_e32 v0, vcc, s23, v60
	s_nop 1
	v_addc_co_u32_e32 v1, vcc, 0, v61, vcc
	global_store_dwordx2 v[0:1], v[2:3], off
	v_add_co_u32_e32 v0, vcc, s33, v60
	s_waitcnt lgkmcnt(0)
	s_barrier
	ds_read_b128 v[120:123], v108 offset:28672
	ds_read_b128 v[124:127], v108 offset:33792
	ds_read_b128 v[128:131], v108 offset:28736
	ds_read_b128 v[132:135], v108 offset:33856
	s_waitcnt lgkmcnt(3)
	v_mfma_f32_16x16x32_bf16 v[120:123], v[16:19], v[120:123], 0
	s_waitcnt lgkmcnt(2)
	v_mfma_f32_16x16x32_bf16 v[124:127], v[16:19], v[124:127], 0
	s_waitcnt lgkmcnt(1)
	v_mfma_f32_16x16x32_bf16 v[120:123], v[20:23], v[128:131], v[120:123]
	s_waitcnt lgkmcnt(0)
	v_mfma_f32_16x16x32_bf16 v[124:127], v[20:23], v[132:135], v[124:127]
	ds_read_b128 v[128:131], v108 offset:28800
	ds_read_b128 v[132:135], v108 offset:33920
	s_waitcnt lgkmcnt(1)
	v_mfma_f32_16x16x32_bf16 v[120:123], v[24:27], v[128:131], v[120:123]
	s_waitcnt lgkmcnt(0)
	v_mfma_f32_16x16x32_bf16 v[124:127], v[24:27], v[132:135], v[124:127]
	ds_read_b128 v[128:131], v108 offset:28864
	ds_read_b128 v[132:135], v108 offset:33984
	s_waitcnt lgkmcnt(1)
	v_mfma_f32_16x16x32_bf16 v[120:123], v[32:35], v[128:131], v[120:123]
	s_waitcnt lgkmcnt(0)
	v_mfma_f32_16x16x32_bf16 v[124:127], v[32:35], v[132:135], v[124:127]
	s_waitcnt lgkmcnt(0)
	s_barrier
	s_nop 1
	v_addc_co_u32_e32 v1, vcc, 0, v61, vcc
	v_add_co_u32_e32 v2, vcc, s44, v60
	s_nop 1
	v_addc_co_u32_e32 v3, vcc, 0, v61, vcc
	global_load_dwordx2 v[58:59], v[0:1], off
	global_load_dwordx2 v[56:57], v[2:3], off
	s_waitcnt vmcnt(10)
	v_mfma_f32_32x32x16_bf16 v[128:143], v[52:55], v[28:31], 0
	v_mfma_f32_32x32x16_bf16 v[144:159], v[52:55], v[40:43], 0
	v_mfma_f32_32x32x16_bf16 v[160:175], v[52:55], v[44:47], 0
	v_mfma_f32_32x32x16_bf16 v[176:191], v[52:55], v[48:51], 0
	s_nop 8
	ds_write_b128 v71, v[128:131]
	ds_write_b128 v71, v[132:135] offset:32
	ds_write_b128 v71, v[136:139] offset:64
	ds_write_b128 v71, v[140:143] offset:96
	ds_write_b128 v71, v[144:147] offset:4608
	ds_write_b128 v71, v[148:151] offset:4640
	ds_write_b128 v71, v[152:155] offset:4672
	ds_write_b128 v71, v[156:159] offset:4704
	ds_write_b128 v71, v[160:163] offset:9216
	ds_write_b128 v71, v[164:167] offset:9248
	ds_write_b128 v71, v[168:171] offset:9280
	ds_write_b128 v71, v[172:175] offset:9312
	ds_write_b128 v71, v[176:179] offset:13824
	ds_write_b128 v71, v[180:183] offset:13856
	ds_write_b128 v71, v[184:187] offset:13888
	ds_write_b128 v71, v[188:191] offset:13920
	v_mov_b32_e32 v0, v120
	v_mov_b32_e32 v1, v121
	v_mov_b32_e32 v2, v122
	v_mov_b32_e32 v3, v123
	v_mov_b32_e32 v4, v124
	v_mov_b32_e32 v5, v125
	v_mov_b32_e32 v6, v126
	v_mov_b32_e32 v7, v127
	s_waitcnt vmcnt(9)
	v_lshlrev_b32_e32 v8, 16, v88
	s_nop 3
	v_fma_f32 v0, v36, v8, v0
	v_and_b32_e32 v8, 0xffff0000, v88
	v_fma_f32 v1, v37, v8, v1
	v_lshlrev_b32_e32 v8, 16, v89
	v_fma_f32 v2, v38, v8, v2
	v_and_b32_e32 v8, 0xffff0000, v89
	v_fmac_f32_e32 v3, v39, v8
	s_waitcnt vmcnt(8)
	v_lshlrev_b32_e32 v8, 16, v90
	v_fma_f32 v4, v36, v8, v4
	v_and_b32_e32 v8, 0xffff0000, v90
	v_fma_f32 v5, v37, v8, v5
	v_lshlrev_b32_e32 v8, 16, v91
	v_fma_f32 v6, v38, v8, v6
	v_and_b32_e32 v8, 0xffff0000, v91
	v_fmac_f32_e32 v7, v39, v8
	v_mul_f32_e32 v8, v0, v0
	v_fmamk_f32 v8, v8, 0xbdd2d3e8, v111
	v_mul_f32_e32 v8, v0, v8
	v_exp_f32_e32 v8, v8
	s_nop 0
	v_add_f32_e32 v8, 1.0, v8
	v_rcp_f32_e32 v8, v8
	s_nop 0
	v_mul_f32_e32 v0, v0, v8
	v_mul_f32_e32 v8, v1, v1
	v_fmamk_f32 v8, v8, 0xbdd2d3e8, v111
	v_mul_f32_e32 v8, v1, v8
	v_exp_f32_e32 v8, v8
	s_nop 0
	v_add_f32_e32 v8, 1.0, v8
	v_rcp_f32_e32 v8, v8
	s_nop 0
	v_mul_f32_e32 v1, v1, v8
	v_cvt_pk_bf16_f32 v0, v0, v1
	v_mul_f32_e32 v1, v2, v2
	v_fmamk_f32 v1, v1, 0xbdd2d3e8, v111
	v_mul_f32_e32 v1, v2, v1
	v_exp_f32_e32 v1, v1
	s_nop 0
	v_add_f32_e32 v1, 1.0, v1
	v_rcp_f32_e32 v1, v1
	s_nop 0
	v_mul_f32_e32 v1, v2, v1
	v_mul_f32_e32 v2, v3, v3
	v_fmamk_f32 v2, v2, 0xbdd2d3e8, v111
	v_mul_f32_e32 v2, v3, v2
	v_exp_f32_e32 v2, v2
	s_nop 0
	v_add_f32_e32 v2, 1.0, v2
	v_rcp_f32_e32 v2, v2
	s_nop 0
	v_mul_f32_e32 v2, v3, v2
	v_cvt_pk_bf16_f32 v1, v1, v2
	v_mul_f32_e32 v2, v4, v4
	v_mul_f32_e32 v3, v5, v5
	v_fmamk_f32 v2, v2, 0xbdd2d3e8, v111
	v_fmamk_f32 v3, v3, 0xbdd2d3e8, v111
	v_mul_f32_e32 v2, v4, v2
	v_mul_f32_e32 v3, v5, v3
	v_exp_f32_e32 v2, v2
	v_exp_f32_e32 v3, v3
	v_add_f32_e32 v2, 1.0, v2
	v_add_f32_e32 v3, 1.0, v3
	v_rcp_f32_e32 v2, v2
	v_rcp_f32_e32 v3, v3
	v_mul_f32_e32 v2, v4, v2
	v_mul_f32_e32 v3, v5, v3
	v_cvt_pk_bf16_f32 v2, v2, v3
	v_mul_f32_e32 v3, v6, v6
	v_mul_f32_e32 v4, v7, v7
	v_fmamk_f32 v3, v3, 0xbdd2d3e8, v111
	v_fmamk_f32 v4, v4, 0xbdd2d3e8, v111
	v_mul_f32_e32 v3, v6, v3
	v_mul_f32_e32 v4, v7, v4
	v_exp_f32_e32 v3, v3
	v_exp_f32_e32 v4, v4
	v_add_f32_e32 v3, 1.0, v3
	v_add_f32_e32 v4, 1.0, v4
	v_rcp_f32_e32 v3, v3
	v_rcp_f32_e32 v4, v4
	v_mul_f32_e32 v3, v6, v3
	v_mul_f32_e32 v4, v7, v4
	v_cvt_pk_bf16_f32 v3, v3, v4
	v_add_co_u32_e32 v4, vcc, s45, v60
	s_nop 1
	v_addc_co_u32_e32 v5, vcc, 0, v61, vcc
	global_store_dwordx2 v[4:5], v[0:1], off
	v_add_co_u32_e32 v0, vcc, s46, v60
	s_nop 1
	v_addc_co_u32_e32 v1, vcc, 0, v61, vcc
	global_store_dwordx2 v[0:1], v[2:3], off
	s_waitcnt lgkmcnt(0)
	s_barrier
	s_waitcnt lgkmcnt(0)
	s_barrier
	ds_read_b128 v[0:3], v108 offset:18432
	ds_read_b128 v[4:7], v108 offset:23552
	ds_read_b128 v[8:11], v108 offset:18496
	ds_read_b128 v[12:15], v108 offset:23616
	s_mov_b32 s4, 0x11d3c000
	s_waitcnt lgkmcnt(3)
	v_mfma_f32_16x16x32_bf16 v[0:3], v[16:19], v[0:3], 0
	s_waitcnt lgkmcnt(2)
	v_mfma_f32_16x16x32_bf16 v[4:7], v[16:19], v[4:7], 0
	s_waitcnt lgkmcnt(1)
	v_mfma_f32_16x16x32_bf16 v[0:3], v[20:23], v[8:11], v[0:3]
	s_waitcnt lgkmcnt(0)
	v_mfma_f32_16x16x32_bf16 v[4:7], v[20:23], v[12:15], v[4:7]
	ds_read_b128 v[8:11], v108 offset:18560
	ds_read_b128 v[12:15], v108 offset:23680
	s_waitcnt lgkmcnt(1)
	v_mfma_f32_16x16x32_bf16 v[0:3], v[24:27], v[8:11], v[0:3]
	s_waitcnt lgkmcnt(0)
	v_mfma_f32_16x16x32_bf16 v[4:7], v[24:27], v[12:15], v[4:7]
	ds_read_b128 v[8:11], v108 offset:18624
	ds_read_b128 v[12:15], v108 offset:23744
	s_waitcnt lgkmcnt(1)
	v_mfma_f32_16x16x32_bf16 v[0:3], v[32:35], v[8:11], v[0:3]
	s_waitcnt vmcnt(7)
	v_lshlrev_b32_e32 v8, 16, v94
	s_waitcnt lgkmcnt(0)
	v_mfma_f32_16x16x32_bf16 v[4:7], v[32:35], v[12:15], v[4:7]
	s_nop 3
	v_fma_f32 v0, v36, v8, v0
	v_and_b32_e32 v8, 0xffff0000, v94
	v_fma_f32 v1, v37, v8, v1
	v_lshlrev_b32_e32 v8, 16, v95
	v_fma_f32 v2, v38, v8, v2
	v_and_b32_e32 v8, 0xffff0000, v95
	v_fmac_f32_e32 v3, v39, v8
	s_waitcnt vmcnt(6)
	v_lshlrev_b32_e32 v8, 16, v62
	v_fma_f32 v4, v36, v8, v4
	v_and_b32_e32 v8, 0xffff0000, v62
	v_fma_f32 v5, v37, v8, v5
	v_lshlrev_b32_e32 v8, 16, v63
	v_fma_f32 v6, v38, v8, v6
	v_and_b32_e32 v8, 0xffff0000, v63
	v_fmac_f32_e32 v7, v39, v8
	v_mul_f32_e32 v8, v0, v0
	v_fmamk_f32 v8, v8, 0xbdd2d3e8, v111
	v_mul_f32_e32 v8, v0, v8
	v_exp_f32_e32 v8, v8
	s_nop 0
	v_add_f32_e32 v8, 1.0, v8
	v_rcp_f32_e32 v8, v8
	s_nop 0
	v_mul_f32_e32 v0, v0, v8
	v_mul_f32_e32 v8, v1, v1
	v_fmamk_f32 v8, v8, 0xbdd2d3e8, v111
	v_mul_f32_e32 v8, v1, v8
	v_exp_f32_e32 v8, v8
	s_nop 0
	v_add_f32_e32 v8, 1.0, v8
	v_rcp_f32_e32 v8, v8
	s_nop 0
	v_mul_f32_e32 v1, v1, v8
	v_cvt_pk_bf16_f32 v0, v0, v1
	v_mul_f32_e32 v1, v2, v2
	v_fmamk_f32 v1, v1, 0xbdd2d3e8, v111
	v_mul_f32_e32 v1, v2, v1
	v_exp_f32_e32 v1, v1
	s_nop 0
	v_add_f32_e32 v1, 1.0, v1
	v_rcp_f32_e32 v1, v1
	s_nop 0
	v_mul_f32_e32 v1, v2, v1
	v_mul_f32_e32 v2, v3, v3
	v_fmamk_f32 v2, v2, 0xbdd2d3e8, v111
	v_mul_f32_e32 v2, v3, v2
	v_exp_f32_e32 v2, v2
	s_nop 0
	v_add_f32_e32 v2, 1.0, v2
	v_rcp_f32_e32 v2, v2
	s_nop 0
	v_mul_f32_e32 v2, v3, v2
	v_cvt_pk_bf16_f32 v1, v1, v2
	v_mul_f32_e32 v2, v4, v4
	v_mul_f32_e32 v3, v5, v5
	v_fmamk_f32 v2, v2, 0xbdd2d3e8, v111
	v_fmamk_f32 v3, v3, 0xbdd2d3e8, v111
	v_mul_f32_e32 v2, v4, v2
	v_mul_f32_e32 v3, v5, v3
	v_exp_f32_e32 v2, v2
	v_exp_f32_e32 v3, v3
	v_add_f32_e32 v2, 1.0, v2
	v_add_f32_e32 v3, 1.0, v3
	v_rcp_f32_e32 v2, v2
	v_rcp_f32_e32 v3, v3
	v_mul_f32_e32 v2, v4, v2
	v_mul_f32_e32 v3, v5, v3
	v_cvt_pk_bf16_f32 v2, v2, v3
	v_mul_f32_e32 v3, v6, v6
	v_mul_f32_e32 v4, v7, v7
	v_fmamk_f32 v3, v3, 0xbdd2d3e8, v111
	v_fmamk_f32 v4, v4, 0xbdd2d3e8, v111
	v_mul_f32_e32 v3, v6, v3
	v_mul_f32_e32 v4, v7, v4
	v_exp_f32_e32 v3, v3
	v_exp_f32_e32 v4, v4
	v_add_f32_e32 v3, 1.0, v3
	v_add_f32_e32 v4, 1.0, v4
	v_rcp_f32_e32 v3, v3
	v_rcp_f32_e32 v4, v4
	v_mul_f32_e32 v3, v6, v3
	v_mul_f32_e32 v4, v7, v4
	v_cvt_pk_bf16_f32 v3, v3, v4
	v_add_co_u32_e32 v4, vcc, s47, v60
	s_nop 1
	v_addc_co_u32_e32 v5, vcc, 0, v61, vcc
	global_store_dwordx2 v[4:5], v[0:1], off
	v_add_co_u32_e32 v0, vcc, s4, v60
	s_nop 1
	v_addc_co_u32_e32 v1, vcc, 0, v61, vcc
	global_store_dwordx2 v[0:1], v[2:3], off
	s_waitcnt lgkmcnt(0)
	s_barrier
	s_waitcnt lgkmcnt(0)
	s_barrier
	ds_read_b128 v[0:3], v108 offset:28672
	ds_read_b128 v[4:7], v108 offset:33792
	ds_read_b128 v[8:11], v108 offset:28736
	ds_read_b128 v[12:15], v108 offset:33856
	s_waitcnt lgkmcnt(3)
	v_mfma_f32_16x16x32_bf16 v[0:3], v[16:19], v[0:3], 0
	s_waitcnt lgkmcnt(2)
	v_mfma_f32_16x16x32_bf16 v[4:7], v[16:19], v[4:7], 0
	s_waitcnt lgkmcnt(1)
	v_mfma_f32_16x16x32_bf16 v[0:3], v[20:23], v[8:11], v[0:3]
	s_waitcnt lgkmcnt(0)
	v_mfma_f32_16x16x32_bf16 v[4:7], v[20:23], v[12:15], v[4:7]
	ds_read_b128 v[8:11], v108 offset:28800
	ds_read_b128 v[12:15], v108 offset:33920
	s_waitcnt lgkmcnt(1)
	v_mfma_f32_16x16x32_bf16 v[0:3], v[24:27], v[8:11], v[0:3]
	s_waitcnt lgkmcnt(0)
	v_mfma_f32_16x16x32_bf16 v[4:7], v[24:27], v[12:15], v[4:7]
	ds_read_b128 v[8:11], v108 offset:28864
	ds_read_b128 v[12:15], v108 offset:33984
	s_waitcnt lgkmcnt(1)
	v_mfma_f32_16x16x32_bf16 v[0:3], v[32:35], v[8:11], v[0:3]
	s_waitcnt vmcnt(5)
	v_lshlrev_b32_e32 v8, 16, v58
	s_waitcnt lgkmcnt(0)
	v_mfma_f32_16x16x32_bf16 v[4:7], v[32:35], v[12:15], v[4:7]
	s_nop 3
	v_fma_f32 v0, v36, v8, v0
	v_and_b32_e32 v8, 0xffff0000, v58
	v_fma_f32 v1, v37, v8, v1
	v_lshlrev_b32_e32 v8, 16, v59
	v_fma_f32 v2, v38, v8, v2
	v_and_b32_e32 v8, 0xffff0000, v59
	v_fmac_f32_e32 v3, v39, v8
	s_waitcnt vmcnt(4)
	v_lshlrev_b32_e32 v8, 16, v56
	v_fma_f32 v4, v36, v8, v4
	v_and_b32_e32 v8, 0xffff0000, v56
	v_fma_f32 v5, v37, v8, v5
	v_lshlrev_b32_e32 v8, 16, v57
	v_fma_f32 v6, v38, v8, v6
	v_and_b32_e32 v8, 0xffff0000, v57
	v_fmac_f32_e32 v7, v39, v8
	v_mul_f32_e32 v8, v0, v0
	v_fmamk_f32 v8, v8, 0xbdd2d3e8, v111
	v_mul_f32_e32 v8, v0, v8
	v_exp_f32_e32 v8, v8
	s_nop 0
	v_add_f32_e32 v8, 1.0, v8
	v_rcp_f32_e32 v8, v8
	s_nop 0
	v_mul_f32_e32 v0, v0, v8
	v_mul_f32_e32 v8, v1, v1
	v_fmamk_f32 v8, v8, 0xbdd2d3e8, v111
	v_mul_f32_e32 v8, v1, v8
	v_exp_f32_e32 v8, v8
	s_nop 0
	v_add_f32_e32 v8, 1.0, v8
	v_rcp_f32_e32 v8, v8
	s_nop 0
	v_mul_f32_e32 v1, v1, v8
	v_cvt_pk_bf16_f32 v0, v0, v1
	v_mul_f32_e32 v1, v2, v2
	v_fmamk_f32 v1, v1, 0xbdd2d3e8, v111
	v_mul_f32_e32 v1, v2, v1
	v_exp_f32_e32 v1, v1
	s_nop 0
	v_add_f32_e32 v1, 1.0, v1
	v_rcp_f32_e32 v1, v1
	s_nop 0
	v_mul_f32_e32 v1, v2, v1
	v_mul_f32_e32 v2, v3, v3
	v_fmamk_f32 v2, v2, 0xbdd2d3e8, v111
	v_mul_f32_e32 v2, v3, v2
	v_exp_f32_e32 v2, v2
	s_nop 0
	v_add_f32_e32 v2, 1.0, v2
	v_rcp_f32_e32 v2, v2
	s_nop 0
	v_mul_f32_e32 v2, v3, v2
	v_cvt_pk_bf16_f32 v1, v1, v2
	v_mul_f32_e32 v2, v4, v4
	v_mul_f32_e32 v3, v5, v5
	v_fmamk_f32 v2, v2, 0xbdd2d3e8, v111
	v_fmamk_f32 v3, v3, 0xbdd2d3e8, v111
	v_mul_f32_e32 v2, v4, v2
	v_mul_f32_e32 v3, v5, v3
	v_exp_f32_e32 v2, v2
	v_exp_f32_e32 v3, v3
	v_add_f32_e32 v2, 1.0, v2
	v_add_f32_e32 v3, 1.0, v3
	v_rcp_f32_e32 v2, v2
	v_rcp_f32_e32 v3, v3
	v_mul_f32_e32 v2, v4, v2
	v_mul_f32_e32 v3, v5, v3
	v_cvt_pk_bf16_f32 v2, v2, v3
	v_mul_f32_e32 v3, v6, v6
	v_mul_f32_e32 v4, v7, v7
	v_fmamk_f32 v3, v3, 0xbdd2d3e8, v111
	v_fmamk_f32 v4, v4, 0xbdd2d3e8, v111
	v_mul_f32_e32 v3, v6, v3
	v_mul_f32_e32 v4, v7, v4
	v_exp_f32_e32 v3, v3
	v_exp_f32_e32 v4, v4
	v_add_f32_e32 v3, 1.0, v3
	v_add_f32_e32 v4, 1.0, v4
	v_rcp_f32_e32 v3, v3
	v_rcp_f32_e32 v4, v4
	v_mul_f32_e32 v3, v6, v3
	v_mul_f32_e32 v4, v7, v4
	v_cvt_pk_bf16_f32 v3, v3, v4
	v_add_co_u32_e32 v4, vcc, 0x11d48000, v60
	s_nop 1
	v_addc_co_u32_e32 v5, vcc, 0, v61, vcc
	global_store_dwordx2 v[4:5], v[0:1], off
	v_add_co_u32_e32 v0, vcc, 0x11d54000, v60
	s_nop 1
	v_addc_co_u32_e32 v1, vcc, 0, v61, vcc
	global_store_dwordx2 v[0:1], v[2:3], off
	s_waitcnt lgkmcnt(0)
	s_barrier
	s_mov_b64 s[12:13], 0

.LBB0_1034:
	s_or_b64 exec, exec, s[0:1]
	v_readlane_b32 s52, v232, 54
	s_add_u32 s78, s92, 0x120000
	v_readlane_b32 s53, v232, 55
	s_addc_u32 s79, s93, 0
	s_and_b64 vcc, exec, s[52:53]
	s_waitcnt lgkmcnt(0)
	s_barrier
	s_cbranch_vccnz .LBB0_1074
	s_lshl_b32 s0, s2, 5
	s_and_b32 s0, s0, 0xe0
	s_ashr_i32 s1, s2, 3
	s_add_i32 s0, s0, s1
	s_and_b32 s25, s1, 7
	s_ashr_i32 s24, s0, 3
	s_cmp_lt_u32 s25, 4
	s_mul_i32 s25, s25, 15
	s_cselect_b64 s[38:39], -1, 0
	s_sub_i32 s4, s25, 60
	s_and_b64 s[0:1], s[38:39], exec
	s_mov_b32 s1, 0x814c115
	s_cselect_b32 s43, s1, 0x94eaaa3
	s_mov_b32 s1, 0xd0478067
	s_cselect_b32 s0, s25, s4
	s_cselect_b32 s42, s1, 0x62bb258e
	s_lshr_b64 s[4:5], s[42:43], s0
	s_mul_i32 s24, s24, 3
	s_bfe_u32 s0, s4, 0x20003
	s_add_i32 s14, s0, s24
	s_and_b32 s51, s4, 7
	s_ashr_i32 s15, s14, 31
	v_mov_b32_e32 v4, v210
	s_movk_i32 s5, 0x100
	s_lshl_b64 s[0:1], s[14:15], 11
	s_lshl_b32 s33, s51, 8
	v_mov_b32_e32 v0, 0
	v_cmp_gt_i32_e32 vcc, s5, v4
	v_ashrrev_i32_e32 v5, 31, v4
	v_mov_b32_e32 v12, 0
	v_mov_b32_e32 v16, 0
	v_mov_b32_e32 v17, 0
	v_mov_b32_e32 v18, 0
	v_mov_b32_e32 v19, 0
	v_mov_b32_e32 v20, 0
	v_mov_b32_e32 v21, 0
	v_mov_b32_e32 v22, 0
	v_mov_b32_e32 v23, 0
	v_mov_b32_e32 v24, 0
	v_mov_b32_e32 v25, 0
	v_mov_b32_e32 v26, 0
	v_mov_b32_e32 v27, 0
	s_and_saveexec_b64 s[40:41], vcc
	s_cbranch_execz .LBB0_1037
	s_lshl_b64 s[26:27], s[0:1], 2
	v_readlane_b32 s28, v233, 37
	v_readlane_b32 s29, v233, 38
	s_add_u32 s5, s28, s26
	s_addc_u32 s27, s29, s27
	s_lshl_b32 s26, s33, 2
	s_add_u32 s26, s5, s26
	s_addc_u32 s27, s27, 0
	v_lshl_add_u64 v[2:3], v[4:5], 2, s[26:27]
	global_load_dword v12, v[2:3], off
.LBB0_1037:
	s_or_b64 exec, exec, s[40:41]
	s_lshl_b64 s[0:1], s[0:1], 2
	s_add_u32 s40, s54, s0
	s_addc_u32 s41, s55, s1
	v_cmp_gt_i32_e64 s[0:1], s33, v4
	v_lshl_add_u64 v[2:3], v[4:5], 2, s[40:41]
	s_and_saveexec_b64 s[44:45], s[0:1]
	s_cbranch_execz .LBB0_1039
	global_load_dword v16, v[2:3], off
.LBB0_1039:
	s_or_b64 exec, exec, s[44:45]
	v_add_u32_e32 v14, 0x200, v4
	v_cmp_gt_i32_e64 s[0:1], s33, v14
	s_and_saveexec_b64 s[44:45], s[0:1]
	s_cbranch_execz .LBB0_1041
	global_load_dword v17, v[2:3], off offset:2048
.LBB0_1041:
	s_or_b64 exec, exec, s[44:45]
	v_add_u32_e32 v6, 0x400, v4
	v_cmp_gt_i32_e64 s[0:1], s33, v6
	v_ashrrev_i32_e32 v7, 31, v6
	s_and_saveexec_b64 s[44:45], s[0:1]
	s_cbranch_execz .LBB0_1043
	v_lshl_add_u64 v[2:3], v[6:7], 2, s[40:41]
	global_load_dword v18, v[2:3], off
.LBB0_1043:
	s_or_b64 exec, exec, s[44:45]
	v_add_u32_e32 v8, 0x600, v4
	v_cmp_gt_i32_e64 s[0:1], s33, v8
	v_ashrrev_i32_e32 v9, 31, v8
	s_and_saveexec_b64 s[44:45], s[0:1]
	s_cbranch_execz .LBB0_1045
	v_lshl_add_u64 v[2:3], v[8:9], 2, s[40:41]
	global_load_dword v19, v[2:3], off

.LBB0_1051:
	v_lshl_add_u64 v[2:3], v[8:9], 2, s[44:45]
	global_load_dword v23, v[2:3], off

.LBB0_1058:
	v_lshl_add_u64 v[6:7], v[8:9], 2, s[0:1]
	global_load_dword v27, v[6:7], off
.LBB0_1059:
	s_or_b64 exec, exec, s[42:43]
	s_waitcnt vmcnt(0)
	v_max3_f32 v0, v16, v17, v18
	v_max_f32_e32 v0, v0, v19
	v_max_f32_e32 v0, 0, v0
	v_max3_f32 v1, v20, v21, v22
	v_max_f32_e32 v1, v1, v23
	v_max3_f32 v2, v24, v25, v26
	v_max_f32_e32 v2, v2, v27
	v_mbcnt_hi_u32_b32 v7, -1, v211
	v_and_b32_e32 v5, 64, v7
	v_add_u32_e32 v8, 64, v5
	v_xor_b32_e32 v5, 1, v7
	v_cmp_lt_i32_e32 vcc, v5, v8
	s_waitcnt vmcnt(0)
	v_max_f32_e32 v9, v12, v12
	v_max_f32_e32 v10, v13, v13
	v_cndmask_b32_e32 v5, v7, v5, vcc
	v_lshlrev_b32_e32 v5, 2, v5
	ds_bpermute_b32 v6, v5, v12
	v_max_f32_e32 v11, v15, v15
	v_and_b32_e32 v3, 63, v4
	s_waitcnt lgkmcnt(0)
	v_max_f32_e32 v6, v6, v6
	v_max_f32_e32 v6, v9, v6
	ds_bpermute_b32 v9, v5, v0
	v_max_f32_e32 v0, v0, v0
	s_waitcnt lgkmcnt(0)
	v_max_f32_e32 v9, v9, v9
	v_max_f32_e32 v0, v0, v9
	ds_bpermute_b32 v9, v5, v13
	s_waitcnt lgkmcnt(0)
	v_max_f32_e32 v9, v9, v9
	v_max_f32_e32 v9, v10, v9
	ds_bpermute_b32 v10, v5, v1
	v_max_f32_e32 v1, v1, v1
	s_waitcnt lgkmcnt(0)
	v_max_f32_e32 v10, v10, v10
	v_max_f32_e32 v1, v1, v10
	ds_bpermute_b32 v10, v5, v15
	ds_bpermute_b32 v5, v5, v2
	v_max_f32_e32 v2, v2, v2
	s_waitcnt lgkmcnt(1)
	v_max_f32_e32 v10, v10, v10
	s_waitcnt lgkmcnt(0)
	v_max_f32_e32 v5, v5, v5
	v_max_f32_e32 v2, v2, v5
	v_xor_b32_e32 v5, 2, v7
	v_cmp_lt_i32_e32 vcc, v5, v8
	v_max_f32_e32 v10, v11, v10
	s_nop 0
	v_cndmask_b32_e32 v5, v7, v5, vcc
	v_lshlrev_b32_e32 v5, 2, v5
	ds_bpermute_b32 v11, v5, v6
	s_waitcnt lgkmcnt(0)
	v_max_f32_e32 v11, v11, v11
	v_max_f32_e32 v6, v6, v11
	ds_bpermute_b32 v11, v5, v0
	s_waitcnt lgkmcnt(0)
	v_max_f32_e32 v11, v11, v11
	v_max_f32_e32 v0, v0, v11
	ds_bpermute_b32 v11, v5, v9
	s_waitcnt lgkmcnt(0)
	v_max_f32_e32 v11, v11, v11
	v_max_f32_e32 v9, v9, v11
	ds_bpermute_b32 v11, v5, v1
	s_waitcnt lgkmcnt(0)
	v_max_f32_e32 v11, v11, v11
	v_max_f32_e32 v1, v1, v11
	ds_bpermute_b32 v11, v5, v10
	ds_bpermute_b32 v5, v5, v2
	s_waitcnt lgkmcnt(1)
	v_max_f32_e32 v11, v11, v11
	s_waitcnt lgkmcnt(0)
	v_max_f32_e32 v5, v5, v5
	v_max_f32_e32 v2, v2, v5
	v_xor_b32_e32 v5, 4, v7
	v_cmp_lt_i32_e32 vcc, v5, v8
	v_max_f32_e32 v10, v10, v11
	s_nop 0
	v_cndmask_b32_e32 v5, v7, v5, vcc
	v_lshlrev_b32_e32 v5, 2, v5
	ds_bpermute_b32 v11, v5, v6
	s_waitcnt lgkmcnt(0)
	v_max_f32_e32 v11, v11, v11
	v_max_f32_e32 v6, v6, v11
	ds_bpermute_b32 v11, v5, v0
	s_waitcnt lgkmcnt(0)
	v_max_f32_e32 v11, v11, v11
	v_max_f32_e32 v0, v0, v11
	ds_bpermute_b32 v11, v5, v9
	s_waitcnt lgkmcnt(0)
	v_max_f32_e32 v11, v11, v11
	v_max_f32_e32 v9, v9, v11
	ds_bpermute_b32 v11, v5, v1
	s_waitcnt lgkmcnt(0)
	v_max_f32_e32 v11, v11, v11
	v_max_f32_e32 v1, v1, v11
	ds_bpermute_b32 v11, v5, v10
	ds_bpermute_b32 v5, v5, v2
	s_waitcnt lgkmcnt(1)
	v_max_f32_e32 v11, v11, v11
	s_waitcnt lgkmcnt(0)
	v_max_f32_e32 v5, v5, v5
	v_max_f32_e32 v2, v2, v5
	v_xor_b32_e32 v5, 8, v7
	v_cmp_lt_i32_e32 vcc, v5, v8
	v_max_f32_e32 v10, v10, v11
	s_nop 0
	v_cndmask_b32_e32 v5, v7, v5, vcc
	v_lshlrev_b32_e32 v5, 2, v5
	ds_bpermute_b32 v11, v5, v6
	s_waitcnt lgkmcnt(0)
	v_max_f32_e32 v11, v11, v11
	v_max_f32_e32 v6, v6, v11
	ds_bpermute_b32 v11, v5, v0
	s_waitcnt lgkmcnt(0)
	v_max_f32_e32 v11, v11, v11
	v_max_f32_e32 v11, v0, v11
	ds_bpermute_b32 v0, v5, v9
	s_waitcnt lgkmcnt(0)
	v_max_f32_e32 v0, v0, v0
	v_max_f32_e32 v9, v9, v0
	ds_bpermute_b32 v0, v5, v1
	s_waitcnt lgkmcnt(0)
	v_max_f32_e32 v0, v0, v0
	v_max_f32_e32 v12, v1, v0
	ds_bpermute_b32 v0, v5, v10
	s_waitcnt lgkmcnt(0)
	v_max_f32_e32 v0, v0, v0
	v_max_f32_e32 v10, v10, v0
	ds_bpermute_b32 v0, v5, v2
	s_waitcnt lgkmcnt(0)
	v_max_f32_e32 v0, v0, v0
	v_max_f32_e32 v13, v2, v0
	v_xor_b32_e32 v0, 16, v7
	v_cmp_lt_i32_e32 vcc, v0, v8
	s_nop 1
	v_cndmask_b32_e32 v0, v7, v0, vcc
	v_lshlrev_b32_e32 v14, 2, v0
	ds_bpermute_b32 v0, v14, v6
	ds_bpermute_b32 v2, v14, v9
	ds_bpermute_b32 v1, v14, v11
	ds_bpermute_b32 v5, v14, v12
	s_waitcnt lgkmcnt(3)
	v_max_f32_e32 v0, v0, v0
	s_waitcnt lgkmcnt(2)
	v_max_f32_e32 v2, v2, v2
	v_max_f32_e32 v0, v6, v0
	v_max_f32_e32 v2, v9, v2
	ds_bpermute_b32 v6, v14, v10
	ds_bpermute_b32 v9, v14, v13
	s_waitcnt lgkmcnt(3)
	v_max_f32_e32 v1, v1, v1
	s_waitcnt lgkmcnt(2)
	v_max_f32_e32 v5, v5, v5
	v_max_f32_e32 v1, v11, v1
	s_waitcnt lgkmcnt(1)
	v_max_f32_e32 v6, v6, v6
	s_waitcnt lgkmcnt(0)
	v_max_f32_e32 v9, v9, v9
	v_max_f32_e32 v6, v10, v6
	v_max_f32_e32 v10, v13, v9
	v_xor_b32_e32 v9, 32, v7
	v_cmp_lt_i32_e32 vcc, v9, v8
	v_max_f32_e32 v5, v12, v5
	s_nop 0
	v_cndmask_b32_e32 v7, v7, v9, vcc
	v_lshlrev_b32_e32 v13, 2, v7
	ds_bpermute_b32 v7, v13, v0
	ds_bpermute_b32 v8, v13, v1
	ds_bpermute_b32 v9, v13, v2
	ds_bpermute_b32 v11, v13, v5
	ds_bpermute_b32 v12, v13, v6
	ds_bpermute_b32 v13, v13, v10
	v_cmp_eq_u32_e32 vcc, 0, v3
	s_and_saveexec_b64 s[0:1], vcc
	s_cbranch_execz .LBB0_1061
	s_waitcnt lgkmcnt(5)
	v_max_f32_e32 v7, v7, v7
	v_max_f32_e32 v0, v0, v0
	v_max_f32_e32 v0, v0, v7
	v_ashrrev_i32_e32 v7, 4, v4
	s_waitcnt lgkmcnt(4)
	v_max_f32_e32 v8, v8, v8
	v_max_f32_e32 v1, v1, v1
	v_add_u32_e32 v7, 0, v7
	v_max_f32_e32 v1, v1, v8
	v_add_u32_e32 v8, 0x22880, v7
	s_waitcnt lgkmcnt(3)
	v_max_f32_e32 v9, v9, v9
	v_max_f32_e32 v2, v2, v2
	ds_write_b32 v8, v0
	v_add_u32_e32 v0, 0x228a0, v7
	s_waitcnt lgkmcnt(3)
	v_max_f32_e32 v11, v11, v11
	v_max_f32_e32 v5, v5, v5
	v_max_f32_e32 v2, v2, v9
	ds_write_b32 v0, v1
	v_add_u32_e32 v0, 0x228c0, v7
	s_waitcnt lgkmcnt(3)
	v_max_f32_e32 v12, v12, v12
	v_max_f32_e32 v6, v6, v6
	v_max_f32_e32 v5, v5, v11
	ds_write_b32 v0, v2
	v_add_u32_e32 v0, 0x228e0, v7
	s_waitcnt lgkmcnt(3)
	v_max_f32_e32 v13, v13, v13
	v_max_f32_e32 v10, v10, v10
	v_max_f32_e32 v6, v6, v12
	ds_write_b32 v0, v5
	v_add_u32_e32 v0, 0x22900, v7
	v_max_f32_e32 v10, v10, v13
	ds_write_b32 v0, v6
	v_add_u32_e32 v0, 0x22920, v7
	ds_write_b32 v0, v10

.LBB0_1177:
	global_load_dword v20, v[2:3], off
	s_or_b64 exec, exec, s[46:47]
	v_cmp_gt_i32_e64 s[0:1], s48, v14
	s_and_saveexec_b64 s[46:47], s[0:1]
	s_cbranch_execz .LBB0_1049
.LBB0_1178:
	global_load_dword v21, v[2:3], off offset:2048
	s_or_b64 exec, exec, s[46:47]
	v_cmp_gt_i32_e64 s[0:1], s48, v6
	s_and_saveexec_b64 s[46:47], s[0:1]
	s_cbranch_execz .LBB0_1050
.LBB0_1179:
	v_lshl_add_u64 v[2:3], v[6:7], 2, s[44:45]
	global_load_dword v22, v[2:3], off
	s_or_b64 exec, exec, s[46:47]
	v_cmp_gt_i32_e64 s[0:1], s48, v8
	s_and_saveexec_b64 s[46:47], s[0:1]
	s_cbranch_execnz .LBB0_1051
	s_branch .LBB0_1052
.LBB0_1180:
	global_load_dword v24, v[10:11], off
	s_or_b64 exec, exec, s[42:43]
	v_cmp_gt_i32_e32 vcc, s5, v14
	s_and_saveexec_b64 s[42:43], vcc
	s_cbranch_execz .LBB0_1056
.LBB0_1181:
	global_load_dword v25, v[10:11], off offset:2048
	s_or_b64 exec, exec, s[42:43]
	v_cmp_gt_i32_e32 vcc, s5, v6
	s_and_saveexec_b64 s[42:43], vcc
	s_cbranch_execz .LBB0_1057
.LBB0_1182:
	v_lshl_add_u64 v[6:7], v[6:7], 2, s[0:1]
	global_load_dword v26, v[6:7], off
	s_or_b64 exec, exec, s[42:43]
	v_cmp_gt_i32_e32 vcc, s5, v8
	s_and_saveexec_b64 s[42:43], vcc
	s_cbranch_execnz .LBB0_1058
	s_branch .LBB0_1059

	.amdhsa_kernel _Z8yoco_fwd6Params
		.amdhsa_group_segment_fixed_size 0
		.amdhsa_private_segment_fixed_size 0
		.amdhsa_kernarg_size 456
		.amdhsa_user_sgpr_count 2
		.amdhsa_user_sgpr_dispatch_ptr 0
		.amdhsa_user_sgpr_queue_ptr 0
		.amdhsa_user_sgpr_kernarg_segment_ptr 1
		.amdhsa_user_sgpr_dispatch_id 0
		.amdhsa_user_sgpr_kernarg_preload_length 0
		.amdhsa_user_sgpr_kernarg_preload_offset 0
		.amdhsa_user_sgpr_private_segment_size 0
		.amdhsa_uses_dynamic_stack 0
		.amdhsa_enable_private_segment 0
		.amdhsa_system_sgpr_workgroup_id_x 1
		.amdhsa_system_sgpr_workgroup_id_y 0
		.amdhsa_system_sgpr_workgroup_id_z 0
		.amdhsa_system_sgpr_workgroup_info 0
		.amdhsa_system_vgpr_workitem_id 2
		.amdhsa_next_free_vgpr 234
		.amdhsa_next_free_sgpr 102
		.amdhsa_accum_offset 236
		.amdhsa_reserve_vcc 1
		.amdhsa_float_round_mode_32 0
		.amdhsa_float_round_mode_16_64 0
		.amdhsa_float_denorm_mode_32 3
		.amdhsa_float_denorm_mode_16_64 3
		.amdhsa_dx10_clamp 1
		.amdhsa_ieee_mode 1
		.amdhsa_fp16_overflow 0
		.amdhsa_tg_split 0
		.amdhsa_exception_fp_ieee_invalid_op 0
		.amdhsa_exception_fp_denorm_src 0
		.amdhsa_exception_fp_ieee_div_zero 0
		.amdhsa_exception_fp_ieee_overflow 0
		.amdhsa_exception_fp_ieee_underflow 0
		.amdhsa_exception_fp_ieee_inexact 0
		.amdhsa_exception_int_div_zero 0
	.end_amdhsa_kernel

amdhsa.kernels:
  - .agpr_count:     0
    .args:
      - .offset:         0
        .size:           200
        .value_kind:     by_value
      - .offset:         200
        .size:           4
        .value_kind:     hidden_block_count_x
      - .offset:         204
        .size:           4
        .value_kind:     hidden_block_count_y
      - .offset:         208
        .size:           4
        .value_kind:     hidden_block_count_z
      - .offset:         212
        .size:           2
        .value_kind:     hidden_group_size_x
      - .offset:         214
        .size:           2
        .value_kind:     hidden_group_size_y
      - .offset:         216
        .size:           2
        .value_kind:     hidden_group_size_z
      - .offset:         218
        .size:           2
        .value_kind:     hidden_remainder_x
      - .offset:         220
        .size:           2
        .value_kind:     hidden_remainder_y
      - .offset:         222
        .size:           2
        .value_kind:     hidden_remainder_z
      - .offset:         240
        .size:           8
        .value_kind:     hidden_global_offset_x
      - .offset:         248
        .size:           8
        .value_kind:     hidden_global_offset_y
      - .offset:         256
        .size:           8
        .value_kind:     hidden_global_offset_z
      - .offset:         264
        .size:           2
        .value_kind:     hidden_grid_dims
      - .offset:         288
        .size:           8
        .value_kind:     hidden_multigrid_sync_arg
      - .offset:         320
        .size:           4
        .value_kind:     hidden_dynamic_lds_size
    .group_segment_fixed_size: 0
    .kernarg_segment_align: 8
    .kernarg_segment_size: 456
    .language:       OpenCL C
    .language_version:
      - 2
      - 0
    .max_flat_workgroup_size: 512
    .name:           _Z8yoco_fwd6Params
    .private_segment_fixed_size: 0
    .sgpr_count:     108
    .sgpr_spill_count: 132
    .symbol:         _Z8yoco_fwd6Params.kd
    .uniform_work_group_size: 1
    .uses_dynamic_stack: false
    .vgpr_count:     234
    .vgpr_spill_count: 0
    .wavefront_size: 64
